# one static s_setprio 1 for waves 0-3 at kernel entry for the whole kernel, every other s_setprio removed, aligned loop heads
# baseline (speedup 1.0000x reference)
; #define LAS __attribute__((address_space(3)))
; __global__ void __launch_bounds__(512) fwd_mega(Params P) {
;     ...
;     const int G = gridDim.x, c = blockIdx.x, tid = threadIdx.x;
;     if (P.ws == nullptr) grid.sync();
;     volatile LAS unsigned* xst = (volatile LAS unsigned*)(lds + 131072);
;     if (tid == 0) { xst[0] = 0u; xst[1] = 0u; xst[2] = 0u; xst[3] = 0u; }
;     __syncthreads();
;     const XcdBarrier xb = xcd_barrier_post((unsigned*)(P.ws + OFF_BAR), xst);
.LBB0_12:
	v_readfirstlane_b32 s2, v218
	s_nop 3
	s_cmp_gt_u32 s2, 0xff
	s_cbranch_scc1 .Lgprio_skip
	s_setprio 1

; #define PG8_STAGE(bufoff, gbase, voff) do { _Pragma("unroll") for (int _i = 0; _i < 2; ++_i) \
;         __builtin_amdgcn_global_load_lds((const unsigned*)((const char*)(gbase) + (voff)[_i]), (LAS unsigned*)(lds + (bufoff) + ldsw + _i * 8192), 16, 0, 0); } while (0)
; #define PG8_LDA(dst, b, h) do { _Pragma("unroll") for (int m = 0; m < 4; ++m) _Pragma("unroll") for (int k = 0; k < 2; ++k) dst[m][k] = *(const LAS bf16x8*)(lds + PG8_SA(b, h) + aoff + m * 2048 + k * 1024); } while (0)
; #define PG8_LDB(dst, b, h) do { _Pragma("unroll") for (int n = 0; n < 2; ++n) _Pragma("unroll") for (int k = 0; k < 2; ++k) dst[n][k] = *(const LAS bf16x8*)(lds + PG8_SB(b, h) + boff + n * 2048 + k * 1024); } while (0)
; #define PG8_MMA(ai, bj, At, Bt) do { __builtin_amdgcn_s_setprio(1); _Pragma("unroll") for (int m = 0; m < 4; ++m) _Pragma("unroll") for (int n = 0; n < 2; ++n) _Pragma("unroll") for (int k = 0; k < 2; ++k) \
;         acc[ai][bj][m][n] = __builtin_amdgcn_mfma_f32_16x16x32_bf16(Bt[n][k], At[m][k], acc[ai][bj][m][n], 0, 0, 0); __builtin_amdgcn_s_setprio(0); } while (0)
; #define PG8_WAIT_V(n) asm volatile("s_waitcnt vmcnt(" #n ")" ::: "memory")
; #define PG8_WAIT_L(n) asm volatile("s_waitcnt lgkmcnt(" #n ")" ::: "memory")
; #define PG8_BAR __builtin_amdgcn_s_barrier()
; #define PG8_SCHED __builtin_amdgcn_sched_barrier(0)
; template <class Epi, class Sched>
; __device__ __forceinline__ void gemm_phase(LAS unsigned char* lds, const Gemm g, const Sched& S, const Epi& E) {
;     ...
;         for (int t = 0; t < nt; t += 2) {
;             const bool last = (t == nt - 2);
;             const char* a1 = cA + (size_t)(t + 1) * kstep;
;             const char* a2 = last ? nA : cA + (size_t)(t + 2) * kstep; const char* b2 = last ? nB : cB + (size_t)(t + 2) * kstep;
;             const char* a3 = a2 + kstep; const char* b3 = b2 + kstep;
;             PG8_LDB(B0, 0, 0); PG8_LDB(B1, 0, 1); PG8_SCHED; PG8_LDA(At, 0, 0); PG8_STAGE(PG8_SA(1, 1), a1 + hstep, voffA);
;             PG8_WAIT_V(8); PG8_WAIT_L(0); PG8_BAR; PG8_MMA(0, 0, At, B0); PG8_MMA(0, 1, At, B1); PG8_BAR; PG8_SCHED;
;             PG8_LDA(At, 0, 1); PG8_STAGE(PG8_SB(0, 0), b2, voffB); PG8_STAGE(PG8_SB(0, 1), b2 + hstep, voffB); PG8_STAGE(PG8_SA(0, 0), a2, voffA);
.LBB0_503:
	s_add_u32 s16, s14, 0xfffc0080
	s_addc_u32 s17, s15, -1
	s_add_i32 s41, 0, 0x10000
	s_cmp_eq_u32 s40, 12
	s_cselect_b32 s19, s7, s17
	s_cselect_b32 s18, s8, s16
	s_cselect_b32 s17, s12, s33
	s_cselect_b32 s16, s13, s21
	s_add_i32 s51, 0, 0x14000
	v_add_u32_e32 v84, s41, v168
	v_add_u32_e32 v170, s51, v168
	ds_read_b128 v[72:75], v84
	ds_read_b128 v[76:79], v84 offset:1024
	ds_read_b128 v[80:83], v84 offset:2048
	ds_read_b128 v[84:87], v84 offset:3072
	ds_read_b128 v[154:157], v170
	ds_read_b128 v[158:161], v170 offset:1024
	ds_read_b128 v[162:165], v170 offset:2048
	ds_read_b128 v[170:173], v170 offset:3072
	v_lshl_add_u64 v[178:179], s[14:15], 0, v[150:151]
	s_add_i32 m0, s26, 0xc000
	ds_read_b128 v[174:177], v169
	ds_read_b128 v[192:195], v169 offset:1024
	ds_read_b128 v[196:199], v169 offset:2048
	ds_read_b128 v[200:203], v169 offset:3072
	ds_read_b128 v[204:207], v169 offset:4096
	ds_read_b128 v[208:211], v169 offset:5120
	ds_read_b128 v[212:215], v169 offset:6144
	ds_read_b128 v[230:233], v169 offset:7168
	global_load_lds_dwordx4 v[178:179], off
	v_lshl_add_u64 v[178:179], s[14:15], 0, v[152:153]
	s_add_i32 m0, s26, 0xe000
	s_nop 0
	global_load_lds_dwordx4 v[178:179], off
	s_waitcnt vmcnt(8)
	s_waitcnt lgkmcnt(0)
	s_barrier
	s_waitcnt lgkmcnt(0)
	v_mfma_f32_16x16x32_bf16 v[140:143], v[72:75], v[174:177], v[140:143]
	v_mfma_f32_16x16x32_bf16 v[136:139], v[80:83], v[174:177], v[136:139]
	v_mfma_f32_16x16x32_bf16 v[124:127], v[72:75], v[196:199], v[124:127]
	v_mfma_f32_16x16x32_bf16 v[120:123], v[80:83], v[196:199], v[120:123]
	v_mfma_f32_16x16x32_bf16 v[108:111], v[72:75], v[204:207], v[108:111]
	v_mfma_f32_16x16x32_bf16 v[104:107], v[80:83], v[204:207], v[104:107]
	v_mfma_f32_16x16x32_bf16 v[92:95], v[72:75], v[212:215], v[92:95]
	v_mfma_f32_16x16x32_bf16 v[88:91], v[80:83], v[212:215], v[88:91]
	v_mfma_f32_16x16x32_bf16 v[140:143], v[76:79], v[192:195], v[140:143]
	v_mfma_f32_16x16x32_bf16 v[136:139], v[84:87], v[192:195], v[136:139]
	v_mfma_f32_16x16x32_bf16 v[124:127], v[76:79], v[200:203], v[124:127]
	v_mfma_f32_16x16x32_bf16 v[120:123], v[84:87], v[200:203], v[120:123]
	v_mfma_f32_16x16x32_bf16 v[108:111], v[76:79], v[208:211], v[108:111]
	v_mfma_f32_16x16x32_bf16 v[104:107], v[84:87], v[208:211], v[104:107]
	v_mfma_f32_16x16x32_bf16 v[92:95], v[76:79], v[230:233], v[92:95]
	v_mfma_f32_16x16x32_bf16 v[88:91], v[84:87], v[230:233], v[88:91]
	v_mfma_f32_16x16x32_bf16 v[132:135], v[154:157], v[174:177], v[132:135]
	v_mfma_f32_16x16x32_bf16 v[128:131], v[162:165], v[174:177], v[128:131]
	v_mfma_f32_16x16x32_bf16 v[116:119], v[154:157], v[196:199], v[116:119]
	v_mfma_f32_16x16x32_bf16 v[112:115], v[162:165], v[196:199], v[112:115]
	v_mfma_f32_16x16x32_bf16 v[100:103], v[154:157], v[204:207], v[100:103]
	v_mfma_f32_16x16x32_bf16 v[96:99], v[162:165], v[204:207], v[96:99]
	v_mfma_f32_16x16x32_bf16 v[68:71], v[154:157], v[212:215], v[68:71]
	v_mfma_f32_16x16x32_bf16 v[64:67], v[162:165], v[212:215], v[64:67]
	v_mfma_f32_16x16x32_bf16 v[132:135], v[158:161], v[192:195], v[132:135]
	v_mfma_f32_16x16x32_bf16 v[128:131], v[170:173], v[192:195], v[128:131]
	v_mfma_f32_16x16x32_bf16 v[116:119], v[158:161], v[200:203], v[116:119]
	v_mfma_f32_16x16x32_bf16 v[112:115], v[170:173], v[200:203], v[112:115]
	v_mfma_f32_16x16x32_bf16 v[100:103], v[158:161], v[208:211], v[100:103]
	v_mfma_f32_16x16x32_bf16 v[96:99], v[170:173], v[208:211], v[96:99]
	v_mfma_f32_16x16x32_bf16 v[68:71], v[158:161], v[230:233], v[68:71]
	v_mfma_f32_16x16x32_bf16 v[64:67], v[170:173], v[230:233], v[64:67]
	s_barrier
	s_add_i32 s41, s41, s23
	v_lshl_add_u64 v[178:179], s[16:17], 0, v[184:185]
	s_mov_b32 m0, s41
	ds_read_b128 v[174:177], v169 offset:16384
	ds_read_b128 v[192:195], v169 offset:17408
	ds_read_b128 v[196:199], v169 offset:18432
	ds_read_b128 v[200:203], v169 offset:19456
	ds_read_b128 v[204:207], v169 offset:20480
	ds_read_b128 v[208:211], v169 offset:21504
	ds_read_b128 v[212:215], v169 offset:22528
	ds_read_b128 v[230:233], v169 offset:23552
	global_load_lds_dwordx4 v[178:179], off
	s_add_i32 m0, s41, 0x2000
	s_add_u32 s42, s16, 0x40000
	v_lshl_add_u64 v[216:217], s[16:17], 0, v[148:149]
	s_addc_u32 s43, s17, 0
	s_add_i32 s41, s51, s23
	global_load_lds_dwordx4 v[216:217], off
	v_lshl_add_u64 v[234:235], s[42:43], 0, v[184:185]
	s_mov_b32 m0, s41
	v_lshl_add_u64 v[236:237], s[18:19], 0, v[146:147]
	global_load_lds_dwordx4 v[234:235], off
	v_lshl_add_u64 v[234:235], s[42:43], 0, v[148:149]
	s_add_i32 m0, s41, 0x2000
	s_nop 0
	global_load_lds_dwordx4 v[234:235], off
	v_lshl_add_u64 v[234:235], s[18:19], 0, v[144:145]
	s_mov_b32 m0, s26
	s_nop 0
	global_load_lds_dwordx4 v[234:235], off
	s_mov_b32 m0, s27
	s_nop 0
	global_load_lds_dwordx4 v[236:237], off
	s_waitcnt vmcnt(8)
	s_waitcnt lgkmcnt(0)
	s_barrier
; #define PG8_STAGE(bufoff, gbase, voff) do { _Pragma("unroll") for (int _i = 0; _i < 2; ++_i) \
;         __builtin_amdgcn_global_load_lds((const unsigned*)((const char*)(gbase) + (voff)[_i]), (LAS unsigned*)(lds + (bufoff) + ldsw + _i * 8192), 16, 0, 0); } while (0)
; #define PG8_LDA(dst, b, h) do { _Pragma("unroll") for (int m = 0; m < 4; ++m) _Pragma("unroll") for (int k = 0; k < 2; ++k) dst[m][k] = *(const LAS bf16x8*)(lds + PG8_SA(b, h) + aoff + m * 2048 + k * 1024); } while (0)
; #define PG8_LDB(dst, b, h) do { _Pragma("unroll") for (int n = 0; n < 2; ++n) _Pragma("unroll") for (int k = 0; k < 2; ++k) dst[n][k] = *(const LAS bf16x8*)(lds + PG8_SB(b, h) + boff + n * 2048 + k * 1024); } while (0)
; #define PG8_MMA(ai, bj, At, Bt) do { __builtin_amdgcn_s_setprio(1); _Pragma("unroll") for (int m = 0; m < 4; ++m) _Pragma("unroll") for (int n = 0; n < 2; ++n) _Pragma("unroll") for (int k = 0; k < 2; ++k) \
;         acc[ai][bj][m][n] = __builtin_amdgcn_mfma_f32_16x16x32_bf16(Bt[n][k], At[m][k], acc[ai][bj][m][n], 0, 0, 0); __builtin_amdgcn_s_setprio(0); } while (0)
; #define PG8_WAIT_V(n) asm volatile("s_waitcnt vmcnt(" #n ")" ::: "memory")
; #define PG8_WAIT_L(n) asm volatile("s_waitcnt lgkmcnt(" #n ")" ::: "memory")
; #define PG8_BAR __builtin_amdgcn_s_barrier()
; #define PG8_SCHED __builtin_amdgcn_sched_barrier(0)
; template <class Epi, class Sched>
; __device__ __forceinline__ void gemm_phase(LAS unsigned char* lds, const Gemm g, const Sched& S, const Epi& E) {
;     ...
;             PG8_WAIT_V(8); PG8_WAIT_L(0); PG8_BAR; PG8_MMA(1, 0, At, B0); PG8_MMA(1, 1, At, B1); PG8_BAR; PG8_SCHED;
;             PG8_LDB(B0, 1, 0); PG8_LDB(B1, 1, 1); PG8_SCHED; PG8_LDA(At, 1, 0); PG8_STAGE(PG8_SA(0, 1), a2 + hstep, voffA);
;             PG8_WAIT_V(8); PG8_WAIT_L(0); PG8_BAR; PG8_MMA(0, 0, At, B0); PG8_MMA(0, 1, At, B1); PG8_BAR; PG8_SCHED;
	s_waitcnt lgkmcnt(0)
	v_mfma_f32_16x16x32_bf16 v[60:63], v[72:75], v[174:177], v[60:63]
	v_mfma_f32_16x16x32_bf16 v[56:59], v[80:83], v[174:177], v[56:59]
	v_mfma_f32_16x16x32_bf16 v[44:47], v[72:75], v[196:199], v[44:47]
	v_mfma_f32_16x16x32_bf16 v[40:43], v[80:83], v[196:199], v[40:43]
	v_mfma_f32_16x16x32_bf16 v[28:31], v[72:75], v[204:207], v[28:31]
	v_mfma_f32_16x16x32_bf16 v[24:27], v[80:83], v[204:207], v[24:27]
	v_mfma_f32_16x16x32_bf16 v[12:15], v[72:75], v[212:215], v[12:15]
	v_mfma_f32_16x16x32_bf16 v[8:11], v[80:83], v[212:215], v[8:11]
	v_mfma_f32_16x16x32_bf16 v[60:63], v[76:79], v[192:195], v[60:63]
	v_mfma_f32_16x16x32_bf16 v[56:59], v[84:87], v[192:195], v[56:59]
	v_mfma_f32_16x16x32_bf16 v[44:47], v[76:79], v[200:203], v[44:47]
	v_mfma_f32_16x16x32_bf16 v[40:43], v[84:87], v[200:203], v[40:43]
	v_mfma_f32_16x16x32_bf16 v[28:31], v[76:79], v[208:211], v[28:31]
	v_mfma_f32_16x16x32_bf16 v[24:27], v[84:87], v[208:211], v[24:27]
	v_mfma_f32_16x16x32_bf16 v[12:15], v[76:79], v[230:233], v[12:15]
	v_mfma_f32_16x16x32_bf16 v[8:11], v[84:87], v[230:233], v[8:11]
	v_mfma_f32_16x16x32_bf16 v[52:55], v[154:157], v[174:177], v[52:55]
	v_mfma_f32_16x16x32_bf16 v[48:51], v[162:165], v[174:177], v[48:51]
	v_mfma_f32_16x16x32_bf16 v[36:39], v[154:157], v[196:199], v[36:39]
	v_mfma_f32_16x16x32_bf16 v[32:35], v[162:165], v[196:199], v[32:35]
	v_mfma_f32_16x16x32_bf16 v[20:23], v[154:157], v[204:207], v[20:23]
	v_mfma_f32_16x16x32_bf16 v[16:19], v[162:165], v[204:207], v[16:19]
	v_mfma_f32_16x16x32_bf16 v[4:7], v[154:157], v[212:215], v[4:7]
	v_mfma_f32_16x16x32_bf16 v[0:3], v[162:165], v[212:215], v[0:3]
	v_mfma_f32_16x16x32_bf16 v[52:55], v[158:161], v[192:195], v[52:55]
	v_mfma_f32_16x16x32_bf16 v[48:51], v[170:173], v[192:195], v[48:51]
	v_mfma_f32_16x16x32_bf16 v[36:39], v[158:161], v[200:203], v[36:39]
	v_mfma_f32_16x16x32_bf16 v[32:35], v[170:173], v[200:203], v[32:35]
	v_mfma_f32_16x16x32_bf16 v[20:23], v[158:161], v[208:211], v[20:23]
	v_mfma_f32_16x16x32_bf16 v[16:19], v[170:173], v[208:211], v[16:19]
	v_mfma_f32_16x16x32_bf16 v[4:7], v[158:161], v[230:233], v[4:7]
	v_mfma_f32_16x16x32_bf16 v[0:3], v[170:173], v[230:233], v[0:3]
	s_barrier
	s_add_i32 s41, 0, 0x18000
	s_add_i32 s42, 0, 0x1c000
	v_add_u32_e32 v84, s41, v168
	v_add_u32_e32 v170, s42, v168
	ds_read_b128 v[72:75], v84
	ds_read_b128 v[76:79], v84 offset:1024
	ds_read_b128 v[80:83], v84 offset:2048
	ds_read_b128 v[84:87], v84 offset:3072
	ds_read_b128 v[154:157], v170
	ds_read_b128 v[158:161], v170 offset:1024
	ds_read_b128 v[162:165], v170 offset:2048
	ds_read_b128 v[170:173], v170 offset:3072
	s_add_u32 s18, s18, 0x40000
	s_addc_u32 s19, s19, 0
	s_mov_b32 m0, s28
	v_lshl_add_u64 v[238:239], s[18:19], 0, v[144:145]
	ds_read_b128 v[174:177], v169 offset:32768
	ds_read_b128 v[192:195], v169 offset:33792
	ds_read_b128 v[196:199], v169 offset:34816
	ds_read_b128 v[200:203], v169 offset:35840
	ds_read_b128 v[204:207], v169 offset:36864
	ds_read_b128 v[208:211], v169 offset:37888
	ds_read_b128 v[212:215], v169 offset:38912
	ds_read_b128 v[230:233], v169 offset:39936
	global_load_lds_dwordx4 v[238:239], off
	v_lshl_add_u64 v[238:239], s[18:19], 0, v[146:147]
	s_mov_b32 m0, s29
	s_nop 0
	global_load_lds_dwordx4 v[238:239], off
	s_waitcnt vmcnt(8)
	s_waitcnt lgkmcnt(0)
	s_barrier
	s_waitcnt lgkmcnt(0)
	v_mfma_f32_16x16x32_bf16 v[140:143], v[72:75], v[174:177], v[140:143]
	v_mfma_f32_16x16x32_bf16 v[136:139], v[80:83], v[174:177], v[136:139]
	v_mfma_f32_16x16x32_bf16 v[124:127], v[72:75], v[196:199], v[124:127]
	v_mfma_f32_16x16x32_bf16 v[120:123], v[80:83], v[196:199], v[120:123]
	v_mfma_f32_16x16x32_bf16 v[108:111], v[72:75], v[204:207], v[108:111]
	v_mfma_f32_16x16x32_bf16 v[104:107], v[80:83], v[204:207], v[104:107]
	v_mfma_f32_16x16x32_bf16 v[92:95], v[72:75], v[212:215], v[92:95]
	v_mfma_f32_16x16x32_bf16 v[88:91], v[80:83], v[212:215], v[88:91]
	v_mfma_f32_16x16x32_bf16 v[140:143], v[76:79], v[192:195], v[140:143]
	v_mfma_f32_16x16x32_bf16 v[136:139], v[84:87], v[192:195], v[136:139]
	v_mfma_f32_16x16x32_bf16 v[124:127], v[76:79], v[200:203], v[124:127]
	v_mfma_f32_16x16x32_bf16 v[120:123], v[84:87], v[200:203], v[120:123]
	v_mfma_f32_16x16x32_bf16 v[108:111], v[76:79], v[208:211], v[108:111]
	v_mfma_f32_16x16x32_bf16 v[104:107], v[84:87], v[208:211], v[104:107]
	v_mfma_f32_16x16x32_bf16 v[92:95], v[76:79], v[230:233], v[92:95]
	v_mfma_f32_16x16x32_bf16 v[88:91], v[84:87], v[230:233], v[88:91]
	v_mfma_f32_16x16x32_bf16 v[132:135], v[154:157], v[174:177], v[132:135]
	v_mfma_f32_16x16x32_bf16 v[128:131], v[162:165], v[174:177], v[128:131]
	v_mfma_f32_16x16x32_bf16 v[116:119], v[154:157], v[196:199], v[116:119]
	v_mfma_f32_16x16x32_bf16 v[112:115], v[162:165], v[196:199], v[112:115]
	v_mfma_f32_16x16x32_bf16 v[100:103], v[154:157], v[204:207], v[100:103]
	v_mfma_f32_16x16x32_bf16 v[96:99], v[162:165], v[204:207], v[96:99]
	v_mfma_f32_16x16x32_bf16 v[68:71], v[154:157], v[212:215], v[68:71]
	v_mfma_f32_16x16x32_bf16 v[64:67], v[162:165], v[212:215], v[64:67]
	v_mfma_f32_16x16x32_bf16 v[132:135], v[158:161], v[192:195], v[132:135]
	v_mfma_f32_16x16x32_bf16 v[128:131], v[170:173], v[192:195], v[128:131]
	v_mfma_f32_16x16x32_bf16 v[116:119], v[158:161], v[200:203], v[116:119]
	v_mfma_f32_16x16x32_bf16 v[112:115], v[170:173], v[200:203], v[112:115]
	v_mfma_f32_16x16x32_bf16 v[100:103], v[158:161], v[208:211], v[100:103]
	v_mfma_f32_16x16x32_bf16 v[96:99], v[170:173], v[208:211], v[96:99]
	v_mfma_f32_16x16x32_bf16 v[68:71], v[158:161], v[230:233], v[68:71]
	v_mfma_f32_16x16x32_bf16 v[64:67], v[170:173], v[230:233], v[64:67]
	s_barrier
; #define PG8_STAGE(bufoff, gbase, voff) do { _Pragma("unroll") for (int _i = 0; _i < 2; ++_i) \
;         __builtin_amdgcn_global_load_lds((const unsigned*)((const char*)(gbase) + (voff)[_i]), (LAS unsigned*)(lds + (bufoff) + ldsw + _i * 8192), 16, 0, 0); } while (0)
; #define PG8_LDA(dst, b, h) do { _Pragma("unroll") for (int m = 0; m < 4; ++m) _Pragma("unroll") for (int k = 0; k < 2; ++k) dst[m][k] = *(const LAS bf16x8*)(lds + PG8_SA(b, h) + aoff + m * 2048 + k * 1024); } while (0)
; #define PG8_MMA(ai, bj, At, Bt) do { __builtin_amdgcn_s_setprio(1); _Pragma("unroll") for (int m = 0; m < 4; ++m) _Pragma("unroll") for (int n = 0; n < 2; ++n) _Pragma("unroll") for (int k = 0; k < 2; ++k) \
;         acc[ai][bj][m][n] = __builtin_amdgcn_mfma_f32_16x16x32_bf16(Bt[n][k], At[m][k], acc[ai][bj][m][n], 0, 0, 0); __builtin_amdgcn_s_setprio(0); } while (0)
; #define PG8_WAIT_V(n) asm volatile("s_waitcnt vmcnt(" #n ")" ::: "memory")
; #define PG8_WAIT_L(n) asm volatile("s_waitcnt lgkmcnt(" #n ")" ::: "memory")
; #define PG8_BAR __builtin_amdgcn_s_barrier()
; #define PG8_SCHED __builtin_amdgcn_sched_barrier(0)
; template <class Epi, class Sched>
; __device__ __forceinline__ void gemm_phase(LAS unsigned char* lds, const Gemm g, const Sched& S, const Epi& E) {
;     ...
;             PG8_LDA(At, 1, 1); PG8_STAGE(PG8_SB(1, 0), b3, voffB); PG8_STAGE(PG8_SB(1, 1), b3 + hstep, voffB); PG8_STAGE(PG8_SA(1, 0), a3, voffA);
;             PG8_WAIT_V(8); PG8_WAIT_L(0); PG8_BAR; PG8_MMA(1, 0, At, B0); PG8_MMA(1, 1, At, B1); PG8_BAR; PG8_SCHED;
;         }
;         if (wr == 0) PG8_BAR;
	s_add_i32 s18, s41, s23
	v_lshl_add_u64 v[178:179], v[178:179], 0, s[84:85]
	s_mov_b32 m0, s18
	ds_read_b128 v[174:177], v169 offset:49152
	ds_read_b128 v[192:195], v169 offset:50176
	ds_read_b128 v[196:199], v169 offset:51200
	ds_read_b128 v[200:203], v169 offset:52224
	ds_read_b128 v[204:207], v169 offset:53248
	ds_read_b128 v[208:211], v169 offset:54272
	ds_read_b128 v[212:215], v169 offset:55296
	ds_read_b128 v[230:233], v169 offset:56320
	global_load_lds_dwordx4 v[178:179], off
	s_add_i32 m0, s18, 0x2000
	s_add_u32 s16, s16, 0x40080
	v_lshl_add_u64 v[178:179], v[216:217], 0, s[84:85]
	s_addc_u32 s17, s17, 0
	s_add_i32 s18, s42, s23
	global_load_lds_dwordx4 v[178:179], off
	v_lshl_add_u64 v[178:179], s[16:17], 0, v[184:185]
	s_mov_b32 m0, s18
	s_nop 0
	global_load_lds_dwordx4 v[178:179], off
	v_lshl_add_u64 v[178:179], s[16:17], 0, v[148:149]
	s_add_i32 m0, s18, 0x2000
	s_nop 0
	global_load_lds_dwordx4 v[178:179], off
	v_lshl_add_u64 v[178:179], v[234:235], 0, s[84:85]
	s_mov_b32 m0, s34
	s_nop 0
	global_load_lds_dwordx4 v[178:179], off
	v_lshl_add_u64 v[178:179], v[236:237], 0, s[84:85]
	s_mov_b32 m0, s35
	s_nop 0
	global_load_lds_dwordx4 v[178:179], off
	s_waitcnt vmcnt(8)
	s_waitcnt lgkmcnt(0)
	s_barrier
	s_waitcnt lgkmcnt(0)
	v_mfma_f32_16x16x32_bf16 v[60:63], v[72:75], v[174:177], v[60:63]
	v_mfma_f32_16x16x32_bf16 v[56:59], v[80:83], v[174:177], v[56:59]
	v_mfma_f32_16x16x32_bf16 v[44:47], v[72:75], v[196:199], v[44:47]
	v_mfma_f32_16x16x32_bf16 v[40:43], v[80:83], v[196:199], v[40:43]
	v_mfma_f32_16x16x32_bf16 v[28:31], v[72:75], v[204:207], v[28:31]
	v_mfma_f32_16x16x32_bf16 v[24:27], v[80:83], v[204:207], v[24:27]
	v_mfma_f32_16x16x32_bf16 v[12:15], v[72:75], v[212:215], v[12:15]
	v_mfma_f32_16x16x32_bf16 v[8:11], v[80:83], v[212:215], v[8:11]
	v_mfma_f32_16x16x32_bf16 v[60:63], v[76:79], v[192:195], v[60:63]
	v_mfma_f32_16x16x32_bf16 v[56:59], v[84:87], v[192:195], v[56:59]
	v_mfma_f32_16x16x32_bf16 v[44:47], v[76:79], v[200:203], v[44:47]
	v_mfma_f32_16x16x32_bf16 v[40:43], v[84:87], v[200:203], v[40:43]
	v_mfma_f32_16x16x32_bf16 v[28:31], v[76:79], v[208:211], v[28:31]
	v_mfma_f32_16x16x32_bf16 v[24:27], v[84:87], v[208:211], v[24:27]
	v_mfma_f32_16x16x32_bf16 v[12:15], v[76:79], v[230:233], v[12:15]
	v_mfma_f32_16x16x32_bf16 v[8:11], v[84:87], v[230:233], v[8:11]
	v_mfma_f32_16x16x32_bf16 v[52:55], v[154:157], v[174:177], v[52:55]
	v_mfma_f32_16x16x32_bf16 v[48:51], v[162:165], v[174:177], v[48:51]
	v_mfma_f32_16x16x32_bf16 v[36:39], v[154:157], v[196:199], v[36:39]
	v_mfma_f32_16x16x32_bf16 v[32:35], v[162:165], v[196:199], v[32:35]
	v_mfma_f32_16x16x32_bf16 v[20:23], v[154:157], v[204:207], v[20:23]
	v_mfma_f32_16x16x32_bf16 v[16:19], v[162:165], v[204:207], v[16:19]
	v_mfma_f32_16x16x32_bf16 v[4:7], v[154:157], v[212:215], v[4:7]
	v_mfma_f32_16x16x32_bf16 v[0:3], v[162:165], v[212:215], v[0:3]
	v_mfma_f32_16x16x32_bf16 v[52:55], v[158:161], v[192:195], v[52:55]
	v_mfma_f32_16x16x32_bf16 v[48:51], v[170:173], v[192:195], v[48:51]
	v_mfma_f32_16x16x32_bf16 v[36:39], v[158:161], v[200:203], v[36:39]
	v_mfma_f32_16x16x32_bf16 v[32:35], v[170:173], v[200:203], v[32:35]
	v_mfma_f32_16x16x32_bf16 v[20:23], v[158:161], v[208:211], v[20:23]
	v_mfma_f32_16x16x32_bf16 v[16:19], v[170:173], v[208:211], v[16:19]
	v_mfma_f32_16x16x32_bf16 v[4:7], v[158:161], v[230:233], v[4:7]
	v_mfma_f32_16x16x32_bf16 v[0:3], v[170:173], v[230:233], v[0:3]
	s_barrier
	s_add_i32 s40, s40, 2
	s_add_u32 s14, s14, 0x100
	s_addc_u32 s15, s15, 0
	s_add_u32 s21, s21, 0x100
	s_addc_u32 s33, s33, 0
	s_cmp_gt_u32 s40, 13
	s_cbranch_scc0 .LBB0_503
	s_and_b64 vcc, exec, s[48:49]
	s_cbranch_vccz .LBB0_506
	s_barrier

; #define PG8_STAGE(bufoff, gbase, voff) do { _Pragma("unroll") for (int _i = 0; _i < 2; ++_i) \
;         __builtin_amdgcn_global_load_lds((const unsigned*)((const char*)(gbase) + (voff)[_i]), (LAS unsigned*)(lds + (bufoff) + ldsw + _i * 8192), 16, 0, 0); } while (0)
; #define PG8_LDA(dst, b, h) do { _Pragma("unroll") for (int m = 0; m < 4; ++m) _Pragma("unroll") for (int k = 0; k < 2; ++k) dst[m][k] = *(const LAS bf16x8*)(lds + PG8_SA(b, h) + aoff + m * 2048 + k * 1024); } while (0)
; #define PG8_LDB(dst, b, h) do { _Pragma("unroll") for (int n = 0; n < 2; ++n) _Pragma("unroll") for (int k = 0; k < 2; ++k) dst[n][k] = *(const LAS bf16x8*)(lds + PG8_SB(b, h) + boff + n * 2048 + k * 1024); } while (0)
; #define PG8_MMA(ai, bj, At, Bt) do { __builtin_amdgcn_s_setprio(1); _Pragma("unroll") for (int m = 0; m < 4; ++m) _Pragma("unroll") for (int n = 0; n < 2; ++n) _Pragma("unroll") for (int k = 0; k < 2; ++k) \
;         acc[ai][bj][m][n] = __builtin_amdgcn_mfma_f32_16x16x32_bf16(Bt[n][k], At[m][k], acc[ai][bj][m][n], 0, 0, 0); __builtin_amdgcn_s_setprio(0); } while (0)
; #define PG8_WAIT_V(n) asm volatile("s_waitcnt vmcnt(" #n ")" ::: "memory")
; #define PG8_WAIT_L(n) asm volatile("s_waitcnt lgkmcnt(" #n ")" ::: "memory")
; #define PG8_BAR __builtin_amdgcn_s_barrier()
; #define PG8_SCHED __builtin_amdgcn_sched_barrier(0)
; template <class Epi, class Sched>
; __device__ __forceinline__ void gemm_phase(LAS unsigned char* lds, const Gemm g, const Sched& S, const Epi& E) {
;     ...
;         for (int t = 0; t < nt; t += 2) {
;             const bool last = (t == nt - 2);
;             const char* a1 = cA + (size_t)(t + 1) * kstep;
;             const char* a2 = last ? nA : cA + (size_t)(t + 2) * kstep; const char* b2 = last ? nB : cB + (size_t)(t + 2) * kstep;
;             const char* a3 = a2 + kstep; const char* b3 = b2 + kstep;
;             PG8_LDB(B0, 0, 0); PG8_LDB(B1, 0, 1); PG8_SCHED; PG8_LDA(At, 0, 0); PG8_STAGE(PG8_SA(1, 1), a1 + hstep, voffA);
;             PG8_WAIT_V(8); PG8_WAIT_L(0); PG8_BAR; PG8_MMA(0, 0, At, B0); PG8_MMA(0, 1, At, B1); PG8_BAR; PG8_SCHED;
;             PG8_LDA(At, 0, 1); PG8_STAGE(PG8_SB(0, 0), b2, voffB); PG8_STAGE(PG8_SB(0, 1), b2 + hstep, voffB); PG8_STAGE(PG8_SA(0, 0), a2, voffA);
.LBB0_599:
	s_add_i32 s19, s17, 2
	s_add_u32 s14, s6, 0x80
	s_addc_u32 s15, s7, 0
	s_add_i32 s33, 0, 0x10000
	s_cmp_eq_u32 s12, s17
	s_cselect_b32 s15, s1, s15
	s_cselect_b32 s14, s0, s14
	s_cselect_b32 s43, s65, s16
	s_cselect_b32 s42, s64, s13
	s_add_i32 s17, 0, 0x14000
	v_add_u32_e32 v140, s33, v231
	v_add_u32_e32 v156, s17, v231
	s_waitcnt lgkmcnt(0)
	ds_read_b128 v[128:131], v140
	ds_read_b128 v[132:135], v140 offset:1024
	ds_read_b128 v[136:139], v140 offset:2048
	ds_read_b128 v[140:143], v140 offset:3072
	ds_read_b128 v[144:147], v156
	ds_read_b128 v[148:151], v156 offset:1024
	ds_read_b128 v[152:155], v156 offset:2048
	ds_read_b128 v[156:159], v156 offset:3072
	v_lshl_add_u64 v[214:215], s[6:7], 0, v[198:199]
	s_add_i32 m0, s29, 0xc000
	ds_read_b128 v[160:163], v232
	ds_read_b128 v[164:167], v232 offset:1024
	ds_read_b128 v[168:171], v232 offset:2048
	ds_read_b128 v[172:175], v232 offset:3072
	ds_read_b128 v[176:179], v232 offset:4096
	ds_read_b128 v[202:205], v232 offset:5120
	ds_read_b128 v[206:209], v232 offset:6144
	ds_read_b128 v[210:213], v232 offset:7168
	global_load_lds_dwordx4 v[214:215], off
	v_lshl_add_u64 v[214:215], s[6:7], 0, v[200:201]
	s_add_i32 m0, s29, 0xe000
	s_nop 0
	global_load_lds_dwordx4 v[214:215], off
	s_waitcnt vmcnt(8)
	s_waitcnt lgkmcnt(0)
	s_barrier
	s_waitcnt lgkmcnt(0)
	v_mfma_f32_16x16x32_bf16 v[124:127], v[128:131], v[160:163], v[124:127]
	v_mfma_f32_16x16x32_bf16 v[120:123], v[136:139], v[160:163], v[120:123]
	v_mfma_f32_16x16x32_bf16 v[116:119], v[128:131], v[168:171], v[116:119]
	v_mfma_f32_16x16x32_bf16 v[112:115], v[136:139], v[168:171], v[112:115]
	v_mfma_f32_16x16x32_bf16 v[104:107], v[128:131], v[176:179], v[104:107]
	v_mfma_f32_16x16x32_bf16 v[96:99], v[136:139], v[176:179], v[96:99]
	v_mfma_f32_16x16x32_bf16 v[88:91], v[128:131], v[206:209], v[88:91]
	v_mfma_f32_16x16x32_bf16 v[80:83], v[136:139], v[206:209], v[80:83]
	v_mfma_f32_16x16x32_bf16 v[124:127], v[132:135], v[164:167], v[124:127]
	v_mfma_f32_16x16x32_bf16 v[120:123], v[140:143], v[164:167], v[120:123]
	v_mfma_f32_16x16x32_bf16 v[116:119], v[132:135], v[172:175], v[116:119]
	v_mfma_f32_16x16x32_bf16 v[112:115], v[140:143], v[172:175], v[112:115]
	v_mfma_f32_16x16x32_bf16 v[104:107], v[132:135], v[202:205], v[104:107]
	v_mfma_f32_16x16x32_bf16 v[96:99], v[140:143], v[202:205], v[96:99]
	v_mfma_f32_16x16x32_bf16 v[88:91], v[132:135], v[210:213], v[88:91]
	v_mfma_f32_16x16x32_bf16 v[80:83], v[140:143], v[210:213], v[80:83]
	v_mfma_f32_16x16x32_bf16 v[108:111], v[144:147], v[160:163], v[108:111]
	v_mfma_f32_16x16x32_bf16 v[100:103], v[152:155], v[160:163], v[100:103]
	v_mfma_f32_16x16x32_bf16 v[92:95], v[144:147], v[168:171], v[92:95]
	v_mfma_f32_16x16x32_bf16 v[84:87], v[152:155], v[168:171], v[84:87]
	v_mfma_f32_16x16x32_bf16 v[76:79], v[144:147], v[176:179], v[76:79]
	v_mfma_f32_16x16x32_bf16 v[72:75], v[152:155], v[176:179], v[72:75]
	v_mfma_f32_16x16x32_bf16 v[68:71], v[144:147], v[206:209], v[68:71]
	v_mfma_f32_16x16x32_bf16 v[64:67], v[152:155], v[206:209], v[64:67]
	v_mfma_f32_16x16x32_bf16 v[108:111], v[148:151], v[164:167], v[108:111]
	v_mfma_f32_16x16x32_bf16 v[100:103], v[156:159], v[164:167], v[100:103]
	v_mfma_f32_16x16x32_bf16 v[92:95], v[148:151], v[172:175], v[92:95]
	v_mfma_f32_16x16x32_bf16 v[84:87], v[156:159], v[172:175], v[84:87]
	v_mfma_f32_16x16x32_bf16 v[76:79], v[148:151], v[202:205], v[76:79]
	v_mfma_f32_16x16x32_bf16 v[72:75], v[156:159], v[202:205], v[72:75]
	v_mfma_f32_16x16x32_bf16 v[68:71], v[148:151], v[210:213], v[68:71]
	v_mfma_f32_16x16x32_bf16 v[64:67], v[156:159], v[210:213], v[64:67]
	s_barrier
	s_add_i32 s33, s33, s28
	v_lshl_add_u64 v[214:215], s[42:43], 0, v[184:185]
	s_mov_b32 m0, s33
	ds_read_b128 v[160:163], v232 offset:16384
	ds_read_b128 v[164:167], v232 offset:17408
	ds_read_b128 v[168:171], v232 offset:18432
	ds_read_b128 v[172:175], v232 offset:19456
	ds_read_b128 v[176:179], v232 offset:20480
	ds_read_b128 v[202:205], v232 offset:21504
	ds_read_b128 v[206:209], v232 offset:22528
	ds_read_b128 v[210:213], v232 offset:23552
	global_load_lds_dwordx4 v[214:215], off
	s_add_i32 m0, s33, 0x2000
	v_lshl_add_u64 v[216:217], s[42:43], 0, v[196:197]
	s_add_u32 s42, s42, s54
	s_addc_u32 s43, s43, 0
	s_add_i32 s17, s17, s28
	global_load_lds_dwordx4 v[216:217], off
	v_lshl_add_u64 v[234:235], s[42:43], 0, v[184:185]
	s_mov_b32 m0, s17
	v_lshl_add_u64 v[236:237], s[42:43], 0, v[196:197]
	global_load_lds_dwordx4 v[234:235], off
	s_add_i32 m0, s17, 0x2000
	v_lshl_add_u64 v[238:239], s[14:15], 0, v[192:193]
	global_load_lds_dwordx4 v[236:237], off
	s_mov_b32 m0, s29
	v_lshl_add_u64 v[240:241], s[14:15], 0, v[194:195]
	global_load_lds_dwordx4 v[238:239], off
	s_mov_b32 m0, s30
	s_nop 0
	global_load_lds_dwordx4 v[240:241], off
	s_waitcnt vmcnt(8)
	s_waitcnt lgkmcnt(0)
	s_barrier
; #define PG8_STAGE(bufoff, gbase, voff) do { _Pragma("unroll") for (int _i = 0; _i < 2; ++_i) \
;         __builtin_amdgcn_global_load_lds((const unsigned*)((const char*)(gbase) + (voff)[_i]), (LAS unsigned*)(lds + (bufoff) + ldsw + _i * 8192), 16, 0, 0); } while (0)
; #define PG8_LDA(dst, b, h) do { _Pragma("unroll") for (int m = 0; m < 4; ++m) _Pragma("unroll") for (int k = 0; k < 2; ++k) dst[m][k] = *(const LAS bf16x8*)(lds + PG8_SA(b, h) + aoff + m * 2048 + k * 1024); } while (0)
; #define PG8_LDB(dst, b, h) do { _Pragma("unroll") for (int n = 0; n < 2; ++n) _Pragma("unroll") for (int k = 0; k < 2; ++k) dst[n][k] = *(const LAS bf16x8*)(lds + PG8_SB(b, h) + boff + n * 2048 + k * 1024); } while (0)
; #define PG8_MMA(ai, bj, At, Bt) do { __builtin_amdgcn_s_setprio(1); _Pragma("unroll") for (int m = 0; m < 4; ++m) _Pragma("unroll") for (int n = 0; n < 2; ++n) _Pragma("unroll") for (int k = 0; k < 2; ++k) \
;         acc[ai][bj][m][n] = __builtin_amdgcn_mfma_f32_16x16x32_bf16(Bt[n][k], At[m][k], acc[ai][bj][m][n], 0, 0, 0); __builtin_amdgcn_s_setprio(0); } while (0)
; #define PG8_WAIT_V(n) asm volatile("s_waitcnt vmcnt(" #n ")" ::: "memory")
; #define PG8_WAIT_L(n) asm volatile("s_waitcnt lgkmcnt(" #n ")" ::: "memory")
; #define PG8_BAR __builtin_amdgcn_s_barrier()
; #define PG8_SCHED __builtin_amdgcn_sched_barrier(0)
; template <class Epi, class Sched>
; __device__ __forceinline__ void gemm_phase(LAS unsigned char* lds, const Gemm g, const Sched& S, const Epi& E) {
;     ...
;             PG8_WAIT_V(8); PG8_WAIT_L(0); PG8_BAR; PG8_MMA(1, 0, At, B0); PG8_MMA(1, 1, At, B1); PG8_BAR; PG8_SCHED;
;             PG8_LDB(B0, 1, 0); PG8_LDB(B1, 1, 1); PG8_SCHED; PG8_LDA(At, 1, 0); PG8_STAGE(PG8_SA(0, 1), a2 + hstep, voffA);
;             PG8_WAIT_V(8); PG8_WAIT_L(0); PG8_BAR; PG8_MMA(0, 0, At, B0); PG8_MMA(0, 1, At, B1); PG8_BAR; PG8_SCHED;
	s_waitcnt lgkmcnt(0)
	v_mfma_f32_16x16x32_bf16 v[60:63], v[128:131], v[160:163], v[60:63]
	v_mfma_f32_16x16x32_bf16 v[56:59], v[136:139], v[160:163], v[56:59]
	v_mfma_f32_16x16x32_bf16 v[52:55], v[128:131], v[168:171], v[52:55]
	v_mfma_f32_16x16x32_bf16 v[48:51], v[136:139], v[168:171], v[48:51]
	v_mfma_f32_16x16x32_bf16 v[36:39], v[128:131], v[176:179], v[36:39]
	v_mfma_f32_16x16x32_bf16 v[32:35], v[136:139], v[176:179], v[32:35]
	v_mfma_f32_16x16x32_bf16 v[20:23], v[128:131], v[206:209], v[20:23]
	v_mfma_f32_16x16x32_bf16 v[16:19], v[136:139], v[206:209], v[16:19]
	v_mfma_f32_16x16x32_bf16 v[60:63], v[132:135], v[164:167], v[60:63]
	v_mfma_f32_16x16x32_bf16 v[56:59], v[140:143], v[164:167], v[56:59]
	v_mfma_f32_16x16x32_bf16 v[52:55], v[132:135], v[172:175], v[52:55]
	v_mfma_f32_16x16x32_bf16 v[48:51], v[140:143], v[172:175], v[48:51]
	v_mfma_f32_16x16x32_bf16 v[36:39], v[132:135], v[202:205], v[36:39]
	v_mfma_f32_16x16x32_bf16 v[32:35], v[140:143], v[202:205], v[32:35]
	v_mfma_f32_16x16x32_bf16 v[20:23], v[132:135], v[210:213], v[20:23]
	v_mfma_f32_16x16x32_bf16 v[16:19], v[140:143], v[210:213], v[16:19]
	v_mfma_f32_16x16x32_bf16 v[44:47], v[144:147], v[160:163], v[44:47]
	v_mfma_f32_16x16x32_bf16 v[40:43], v[152:155], v[160:163], v[40:43]
	v_mfma_f32_16x16x32_bf16 v[28:31], v[144:147], v[168:171], v[28:31]
	v_mfma_f32_16x16x32_bf16 v[24:27], v[152:155], v[168:171], v[24:27]
	v_mfma_f32_16x16x32_bf16 v[12:15], v[144:147], v[176:179], v[12:15]
	v_mfma_f32_16x16x32_bf16 v[8:11], v[152:155], v[176:179], v[8:11]
	v_mfma_f32_16x16x32_bf16 v[4:7], v[144:147], v[206:209], v[4:7]
	v_mfma_f32_16x16x32_bf16 v[0:3], v[152:155], v[206:209], v[0:3]
	v_mfma_f32_16x16x32_bf16 v[44:47], v[148:151], v[164:167], v[44:47]
	v_mfma_f32_16x16x32_bf16 v[40:43], v[156:159], v[164:167], v[40:43]
	v_mfma_f32_16x16x32_bf16 v[28:31], v[148:151], v[172:175], v[28:31]
	v_mfma_f32_16x16x32_bf16 v[24:27], v[156:159], v[172:175], v[24:27]
	v_mfma_f32_16x16x32_bf16 v[12:15], v[148:151], v[202:205], v[12:15]
	v_mfma_f32_16x16x32_bf16 v[8:11], v[156:159], v[202:205], v[8:11]
	v_mfma_f32_16x16x32_bf16 v[4:7], v[148:151], v[210:213], v[4:7]
	v_mfma_f32_16x16x32_bf16 v[0:3], v[156:159], v[210:213], v[0:3]
	s_barrier
	s_add_i32 s17, 0, 0x18000
	s_add_i32 s33, 0, 0x1c000
	v_add_u32_e32 v140, s17, v231
	v_add_u32_e32 v156, s33, v231
	ds_read_b128 v[128:131], v140
	ds_read_b128 v[132:135], v140 offset:1024
	ds_read_b128 v[136:139], v140 offset:2048
	ds_read_b128 v[140:143], v140 offset:3072
	ds_read_b128 v[144:147], v156
	ds_read_b128 v[148:151], v156 offset:1024
	ds_read_b128 v[152:155], v156 offset:2048
	ds_read_b128 v[156:159], v156 offset:3072
	s_add_u32 s14, s14, s54
	s_addc_u32 s15, s15, 0
	s_mov_b32 m0, s31
	v_lshl_add_u64 v[242:243], s[14:15], 0, v[192:193]
	ds_read_b128 v[160:163], v232 offset:32768
	ds_read_b128 v[164:167], v232 offset:33792
	ds_read_b128 v[168:171], v232 offset:34816
	ds_read_b128 v[172:175], v232 offset:35840
	ds_read_b128 v[176:179], v232 offset:36864
	ds_read_b128 v[202:205], v232 offset:37888
	ds_read_b128 v[206:209], v232 offset:38912
	ds_read_b128 v[210:213], v232 offset:39936
	global_load_lds_dwordx4 v[242:243], off
	v_lshl_add_u64 v[242:243], s[14:15], 0, v[194:195]
	s_mov_b32 m0, s34
	s_nop 0
	global_load_lds_dwordx4 v[242:243], off
	s_waitcnt vmcnt(8)
	s_waitcnt lgkmcnt(0)
	s_barrier
	s_waitcnt lgkmcnt(0)
	v_mfma_f32_16x16x32_bf16 v[124:127], v[128:131], v[160:163], v[124:127]
	v_mfma_f32_16x16x32_bf16 v[120:123], v[136:139], v[160:163], v[120:123]
	v_mfma_f32_16x16x32_bf16 v[116:119], v[128:131], v[168:171], v[116:119]
	v_mfma_f32_16x16x32_bf16 v[112:115], v[136:139], v[168:171], v[112:115]
	v_mfma_f32_16x16x32_bf16 v[104:107], v[128:131], v[176:179], v[104:107]
	v_mfma_f32_16x16x32_bf16 v[96:99], v[136:139], v[176:179], v[96:99]
	v_mfma_f32_16x16x32_bf16 v[88:91], v[128:131], v[206:209], v[88:91]
	v_mfma_f32_16x16x32_bf16 v[80:83], v[136:139], v[206:209], v[80:83]
	v_mfma_f32_16x16x32_bf16 v[124:127], v[132:135], v[164:167], v[124:127]
	v_mfma_f32_16x16x32_bf16 v[120:123], v[140:143], v[164:167], v[120:123]
	v_mfma_f32_16x16x32_bf16 v[116:119], v[132:135], v[172:175], v[116:119]
	v_mfma_f32_16x16x32_bf16 v[112:115], v[140:143], v[172:175], v[112:115]
	v_mfma_f32_16x16x32_bf16 v[104:107], v[132:135], v[202:205], v[104:107]
	v_mfma_f32_16x16x32_bf16 v[96:99], v[140:143], v[202:205], v[96:99]
	v_mfma_f32_16x16x32_bf16 v[88:91], v[132:135], v[210:213], v[88:91]
	v_mfma_f32_16x16x32_bf16 v[80:83], v[140:143], v[210:213], v[80:83]
	v_mfma_f32_16x16x32_bf16 v[108:111], v[144:147], v[160:163], v[108:111]
	v_mfma_f32_16x16x32_bf16 v[100:103], v[152:155], v[160:163], v[100:103]
	v_mfma_f32_16x16x32_bf16 v[92:95], v[144:147], v[168:171], v[92:95]
	v_mfma_f32_16x16x32_bf16 v[84:87], v[152:155], v[168:171], v[84:87]
	v_mfma_f32_16x16x32_bf16 v[76:79], v[144:147], v[176:179], v[76:79]
	v_mfma_f32_16x16x32_bf16 v[72:75], v[152:155], v[176:179], v[72:75]
	v_mfma_f32_16x16x32_bf16 v[68:71], v[144:147], v[206:209], v[68:71]
	v_mfma_f32_16x16x32_bf16 v[64:67], v[152:155], v[206:209], v[64:67]
	v_mfma_f32_16x16x32_bf16 v[108:111], v[148:151], v[164:167], v[108:111]
	v_mfma_f32_16x16x32_bf16 v[100:103], v[156:159], v[164:167], v[100:103]
	v_mfma_f32_16x16x32_bf16 v[92:95], v[148:151], v[172:175], v[92:95]
	v_mfma_f32_16x16x32_bf16 v[84:87], v[156:159], v[172:175], v[84:87]
	v_mfma_f32_16x16x32_bf16 v[76:79], v[148:151], v[202:205], v[76:79]
	v_mfma_f32_16x16x32_bf16 v[72:75], v[156:159], v[202:205], v[72:75]
	v_mfma_f32_16x16x32_bf16 v[68:71], v[148:151], v[210:213], v[68:71]
	v_mfma_f32_16x16x32_bf16 v[64:67], v[156:159], v[210:213], v[64:67]
	s_barrier
; #define PG8_STAGE(bufoff, gbase, voff) do { _Pragma("unroll") for (int _i = 0; _i < 2; ++_i) \
;         __builtin_amdgcn_global_load_lds((const unsigned*)((const char*)(gbase) + (voff)[_i]), (LAS unsigned*)(lds + (bufoff) + ldsw + _i * 8192), 16, 0, 0); } while (0)
; #define PG8_LDA(dst, b, h) do { _Pragma("unroll") for (int m = 0; m < 4; ++m) _Pragma("unroll") for (int k = 0; k < 2; ++k) dst[m][k] = *(const LAS bf16x8*)(lds + PG8_SA(b, h) + aoff + m * 2048 + k * 1024); } while (0)
; #define PG8_MMA(ai, bj, At, Bt) do { __builtin_amdgcn_s_setprio(1); _Pragma("unroll") for (int m = 0; m < 4; ++m) _Pragma("unroll") for (int n = 0; n < 2; ++n) _Pragma("unroll") for (int k = 0; k < 2; ++k) \
;         acc[ai][bj][m][n] = __builtin_amdgcn_mfma_f32_16x16x32_bf16(Bt[n][k], At[m][k], acc[ai][bj][m][n], 0, 0, 0); __builtin_amdgcn_s_setprio(0); } while (0)
; #define PG8_WAIT_V(n) asm volatile("s_waitcnt vmcnt(" #n ")" ::: "memory")
; #define PG8_WAIT_L(n) asm volatile("s_waitcnt lgkmcnt(" #n ")" ::: "memory")
; #define PG8_BAR __builtin_amdgcn_s_barrier()
; #define PG8_SCHED __builtin_amdgcn_sched_barrier(0)
; template <class Epi, class Sched>
; __device__ __forceinline__ void gemm_phase(LAS unsigned char* lds, const Gemm g, const Sched& S, const Epi& E) {
;     ...
;             PG8_LDA(At, 1, 1); PG8_STAGE(PG8_SB(1, 0), b3, voffB); PG8_STAGE(PG8_SB(1, 1), b3 + hstep, voffB); PG8_STAGE(PG8_SA(1, 0), a3, voffA);
;             PG8_WAIT_V(8); PG8_WAIT_L(0); PG8_BAR; PG8_MMA(1, 0, At, B0); PG8_MMA(1, 1, At, B1); PG8_BAR; PG8_SCHED;
;         }
;         if (wr == 0) PG8_BAR;
	s_add_i32 s14, s17, s28
	v_lshl_add_u64 v[214:215], v[214:215], 0, s[84:85]
	s_mov_b32 m0, s14
	ds_read_b128 v[160:163], v232 offset:49152
	ds_read_b128 v[164:167], v232 offset:50176
	ds_read_b128 v[168:171], v232 offset:51200
	ds_read_b128 v[172:175], v232 offset:52224
	ds_read_b128 v[176:179], v232 offset:53248
	ds_read_b128 v[202:205], v232 offset:54272
	ds_read_b128 v[206:209], v232 offset:55296
	ds_read_b128 v[210:213], v232 offset:56320
	global_load_lds_dwordx4 v[214:215], off
	v_lshl_add_u64 v[214:215], v[216:217], 0, s[84:85]
	s_add_i32 m0, s14, 0x2000
	s_add_i32 s14, s33, s28
	global_load_lds_dwordx4 v[214:215], off
	v_lshl_add_u64 v[214:215], v[234:235], 0, s[84:85]
	s_mov_b32 m0, s14
	s_nop 0
	global_load_lds_dwordx4 v[214:215], off
	v_lshl_add_u64 v[214:215], v[236:237], 0, s[84:85]
	s_add_i32 m0, s14, 0x2000
	s_nop 0
	global_load_lds_dwordx4 v[214:215], off
	v_lshl_add_u64 v[214:215], v[238:239], 0, s[84:85]
	s_mov_b32 m0, s66
	s_nop 0
	global_load_lds_dwordx4 v[214:215], off
	v_lshl_add_u64 v[214:215], v[240:241], 0, s[84:85]
	s_mov_b32 m0, s67
	s_nop 0
	global_load_lds_dwordx4 v[214:215], off
	s_waitcnt vmcnt(8)
	s_waitcnt lgkmcnt(0)
	s_barrier
	s_waitcnt lgkmcnt(0)
	v_mfma_f32_16x16x32_bf16 v[60:63], v[128:131], v[160:163], v[60:63]
	v_mfma_f32_16x16x32_bf16 v[56:59], v[136:139], v[160:163], v[56:59]
	v_mfma_f32_16x16x32_bf16 v[52:55], v[128:131], v[168:171], v[52:55]
	v_mfma_f32_16x16x32_bf16 v[48:51], v[136:139], v[168:171], v[48:51]
	v_mfma_f32_16x16x32_bf16 v[36:39], v[128:131], v[176:179], v[36:39]
	v_mfma_f32_16x16x32_bf16 v[32:35], v[136:139], v[176:179], v[32:35]
	v_mfma_f32_16x16x32_bf16 v[20:23], v[128:131], v[206:209], v[20:23]
	v_mfma_f32_16x16x32_bf16 v[16:19], v[136:139], v[206:209], v[16:19]
	v_mfma_f32_16x16x32_bf16 v[60:63], v[132:135], v[164:167], v[60:63]
	v_mfma_f32_16x16x32_bf16 v[56:59], v[140:143], v[164:167], v[56:59]
	v_mfma_f32_16x16x32_bf16 v[52:55], v[132:135], v[172:175], v[52:55]
	v_mfma_f32_16x16x32_bf16 v[48:51], v[140:143], v[172:175], v[48:51]
	v_mfma_f32_16x16x32_bf16 v[36:39], v[132:135], v[202:205], v[36:39]
	v_mfma_f32_16x16x32_bf16 v[32:35], v[140:143], v[202:205], v[32:35]
	v_mfma_f32_16x16x32_bf16 v[20:23], v[132:135], v[210:213], v[20:23]
	v_mfma_f32_16x16x32_bf16 v[16:19], v[140:143], v[210:213], v[16:19]
	v_mfma_f32_16x16x32_bf16 v[44:47], v[144:147], v[160:163], v[44:47]
	v_mfma_f32_16x16x32_bf16 v[40:43], v[152:155], v[160:163], v[40:43]
	v_mfma_f32_16x16x32_bf16 v[28:31], v[144:147], v[168:171], v[28:31]
	v_mfma_f32_16x16x32_bf16 v[24:27], v[152:155], v[168:171], v[24:27]
	v_mfma_f32_16x16x32_bf16 v[12:15], v[144:147], v[176:179], v[12:15]
	v_mfma_f32_16x16x32_bf16 v[8:11], v[152:155], v[176:179], v[8:11]
	v_mfma_f32_16x16x32_bf16 v[4:7], v[144:147], v[206:209], v[4:7]
	v_mfma_f32_16x16x32_bf16 v[0:3], v[152:155], v[206:209], v[0:3]
	v_mfma_f32_16x16x32_bf16 v[44:47], v[148:151], v[164:167], v[44:47]
	v_mfma_f32_16x16x32_bf16 v[40:43], v[156:159], v[164:167], v[40:43]
	v_mfma_f32_16x16x32_bf16 v[28:31], v[148:151], v[172:175], v[28:31]
	v_mfma_f32_16x16x32_bf16 v[24:27], v[156:159], v[172:175], v[24:27]
	v_mfma_f32_16x16x32_bf16 v[12:15], v[148:151], v[202:205], v[12:15]
	v_mfma_f32_16x16x32_bf16 v[8:11], v[156:159], v[202:205], v[8:11]
	v_mfma_f32_16x16x32_bf16 v[4:7], v[148:151], v[210:213], v[4:7]
	v_mfma_f32_16x16x32_bf16 v[0:3], v[156:159], v[210:213], v[0:3]
	s_barrier
	s_add_u32 s6, s6, 0x100
	s_addc_u32 s7, s7, 0
	s_add_u32 s13, s13, 0x100
	s_addc_u32 s16, s16, 0
	s_cmp_ge_u32 s19, s8
	s_mov_b32 s17, s19
	s_cbranch_scc0 .LBB0_599
	s_and_b64 vcc, exec, s[62:63]
	s_cbranch_vccz .LBB0_602
	s_barrier

; #define PG8_STAGE(bufoff, gbase, voff) do { _Pragma("unroll") for (int _i = 0; _i < 2; ++_i) \
;         __builtin_amdgcn_global_load_lds((const unsigned*)((const char*)(gbase) + (voff)[_i]), (LAS unsigned*)(lds + (bufoff) + ldsw + _i * 8192), 16, 0, 0); } while (0)
; #define PG8_LDA(dst, b, h) do { _Pragma("unroll") for (int m = 0; m < 4; ++m) _Pragma("unroll") for (int k = 0; k < 2; ++k) dst[m][k] = *(const LAS bf16x8*)(lds + PG8_SA(b, h) + aoff + m * 2048 + k * 1024); } while (0)
; #define PG8_LDB(dst, b, h) do { _Pragma("unroll") for (int n = 0; n < 2; ++n) _Pragma("unroll") for (int k = 0; k < 2; ++k) dst[n][k] = *(const LAS bf16x8*)(lds + PG8_SB(b, h) + boff + n * 2048 + k * 1024); } while (0)
; #define PG8_MMA(ai, bj, At, Bt) do { __builtin_amdgcn_s_setprio(1); _Pragma("unroll") for (int m = 0; m < 4; ++m) _Pragma("unroll") for (int n = 0; n < 2; ++n) _Pragma("unroll") for (int k = 0; k < 2; ++k) \
;         acc[ai][bj][m][n] = __builtin_amdgcn_mfma_f32_16x16x32_bf16(Bt[n][k], At[m][k], acc[ai][bj][m][n], 0, 0, 0); __builtin_amdgcn_s_setprio(0); } while (0)
; #define PG8_WAIT_V(n) asm volatile("s_waitcnt vmcnt(" #n ")" ::: "memory")
; #define PG8_WAIT_L(n) asm volatile("s_waitcnt lgkmcnt(" #n ")" ::: "memory")
; #define PG8_BAR __builtin_amdgcn_s_barrier()
; #define PG8_SCHED __builtin_amdgcn_sched_barrier(0)
; template <class Epi, class Sched>
; __device__ __forceinline__ void gemm_phase(LAS unsigned char* lds, const Gemm g, const Sched& S, const Epi& E) {
;     ...
;         for (int t = 0; t < nt; t += 2) {
;             const bool last = (t == nt - 2);
;             const char* a1 = cA + (size_t)(t + 1) * kstep;
;             const char* a2 = last ? nA : cA + (size_t)(t + 2) * kstep; const char* b2 = last ? nB : cB + (size_t)(t + 2) * kstep;
;             const char* a3 = a2 + kstep; const char* b3 = b2 + kstep;
;             PG8_LDB(B0, 0, 0); PG8_LDB(B1, 0, 1); PG8_SCHED; PG8_LDA(At, 0, 0); PG8_STAGE(PG8_SA(1, 1), a1 + hstep, voffA);
;             PG8_WAIT_V(8); PG8_WAIT_L(0); PG8_BAR; PG8_MMA(0, 0, At, B0); PG8_MMA(0, 1, At, B1); PG8_BAR; PG8_SCHED;
;             PG8_LDA(At, 0, 1); PG8_STAGE(PG8_SB(0, 0), b2, voffB); PG8_STAGE(PG8_SB(0, 1), b2 + hstep, voffB); PG8_STAGE(PG8_SA(0, 0), a2, voffA);
.LBB0_744:
	s_add_u32 s24, s22, 0xfffc0080
	s_addc_u32 s25, s23, -1
	s_add_i32 s49, 0, 0x10000
	s_cmp_eq_u32 s48, 12
	s_cselect_b32 s27, s15, s25
	s_cselect_b32 s26, s44, s24
	s_cselect_b32 s25, s17, s47
	s_cselect_b32 s24, s45, s46
	s_add_i32 s52, 0, 0x14000
	v_add_u32_e32 v140, s49, v162
	v_add_u32_e32 v158, s52, v162
	ds_read_b128 v[128:131], v140
	ds_read_b128 v[132:135], v140 offset:1024
	ds_read_b128 v[136:139], v140 offset:2048
	ds_read_b128 v[140:143], v140 offset:3072
	ds_read_b128 v[154:157], v158
	ds_read_b128 v[164:167], v158 offset:1024
	ds_read_b128 v[168:171], v158 offset:2048
	ds_read_b128 v[172:175], v158 offset:3072
	v_lshl_add_u64 v[158:159], s[22:23], 0, v[150:151]
	s_add_i32 m0, s28, 0xc000
	ds_read_b128 v[176:179], v163
	ds_read_b128 v[192:195], v163 offset:1024
	ds_read_b128 v[196:199], v163 offset:2048
	ds_read_b128 v[200:203], v163 offset:3072
	ds_read_b128 v[204:207], v163 offset:4096
	ds_read_b128 v[208:211], v163 offset:5120
	ds_read_b128 v[212:215], v163 offset:6144
	ds_read_b128 v[230:233], v163 offset:7168
	global_load_lds_dwordx4 v[158:159], off
	v_lshl_add_u64 v[158:159], s[22:23], 0, v[152:153]
	s_add_i32 m0, s28, 0xe000
	s_nop 0
	global_load_lds_dwordx4 v[158:159], off
	s_waitcnt vmcnt(8)
	s_waitcnt lgkmcnt(0)
	s_barrier
	s_waitcnt lgkmcnt(0)
	v_mfma_f32_16x16x32_bf16 v[124:127], v[128:131], v[176:179], v[124:127]
	v_mfma_f32_16x16x32_bf16 v[120:123], v[136:139], v[176:179], v[120:123]
	v_mfma_f32_16x16x32_bf16 v[108:111], v[128:131], v[196:199], v[108:111]
	v_mfma_f32_16x16x32_bf16 v[104:107], v[136:139], v[196:199], v[104:107]
	v_mfma_f32_16x16x32_bf16 v[92:95], v[128:131], v[204:207], v[92:95]
	v_mfma_f32_16x16x32_bf16 v[88:91], v[136:139], v[204:207], v[88:91]
	v_mfma_f32_16x16x32_bf16 v[76:79], v[128:131], v[212:215], v[76:79]
	v_mfma_f32_16x16x32_bf16 v[72:75], v[136:139], v[212:215], v[72:75]
	v_mfma_f32_16x16x32_bf16 v[124:127], v[132:135], v[192:195], v[124:127]
	v_mfma_f32_16x16x32_bf16 v[120:123], v[140:143], v[192:195], v[120:123]
	v_mfma_f32_16x16x32_bf16 v[108:111], v[132:135], v[200:203], v[108:111]
	v_mfma_f32_16x16x32_bf16 v[104:107], v[140:143], v[200:203], v[104:107]
	v_mfma_f32_16x16x32_bf16 v[92:95], v[132:135], v[208:211], v[92:95]
	v_mfma_f32_16x16x32_bf16 v[88:91], v[140:143], v[208:211], v[88:91]
	v_mfma_f32_16x16x32_bf16 v[76:79], v[132:135], v[230:233], v[76:79]
	v_mfma_f32_16x16x32_bf16 v[72:75], v[140:143], v[230:233], v[72:75]
	v_mfma_f32_16x16x32_bf16 v[112:115], v[154:157], v[176:179], v[112:115]
	v_mfma_f32_16x16x32_bf16 v[116:119], v[168:171], v[176:179], v[116:119]
	v_mfma_f32_16x16x32_bf16 v[96:99], v[154:157], v[196:199], v[96:99]
	v_mfma_f32_16x16x32_bf16 v[100:103], v[168:171], v[196:199], v[100:103]
	v_mfma_f32_16x16x32_bf16 v[80:83], v[154:157], v[204:207], v[80:83]
	v_mfma_f32_16x16x32_bf16 v[84:87], v[168:171], v[204:207], v[84:87]
	v_mfma_f32_16x16x32_bf16 v[64:67], v[154:157], v[212:215], v[64:67]
	v_mfma_f32_16x16x32_bf16 v[68:71], v[168:171], v[212:215], v[68:71]
	v_mfma_f32_16x16x32_bf16 v[112:115], v[164:167], v[192:195], v[112:115]
	v_mfma_f32_16x16x32_bf16 v[116:119], v[172:175], v[192:195], v[116:119]
	v_mfma_f32_16x16x32_bf16 v[96:99], v[164:167], v[200:203], v[96:99]
	v_mfma_f32_16x16x32_bf16 v[100:103], v[172:175], v[200:203], v[100:103]
	v_mfma_f32_16x16x32_bf16 v[80:83], v[164:167], v[208:211], v[80:83]
	v_mfma_f32_16x16x32_bf16 v[84:87], v[172:175], v[208:211], v[84:87]
	v_mfma_f32_16x16x32_bf16 v[64:67], v[164:167], v[230:233], v[64:67]
	v_mfma_f32_16x16x32_bf16 v[68:71], v[172:175], v[230:233], v[68:71]
	s_barrier
	s_add_i32 s49, s49, s8
	v_lshl_add_u64 v[158:159], s[24:25], 0, v[184:185]
	s_mov_b32 m0, s49
	ds_read_b128 v[176:179], v163 offset:16384
	ds_read_b128 v[192:195], v163 offset:17408
	ds_read_b128 v[196:199], v163 offset:18432
	ds_read_b128 v[200:203], v163 offset:19456
	ds_read_b128 v[204:207], v163 offset:20480
	ds_read_b128 v[208:211], v163 offset:21504
	ds_read_b128 v[212:215], v163 offset:22528
	ds_read_b128 v[230:233], v163 offset:23552
	global_load_lds_dwordx4 v[158:159], off
	s_add_i32 m0, s49, 0x2000
	s_add_u32 s50, s24, 0x40000
	v_lshl_add_u64 v[216:217], s[24:25], 0, v[144:145]
	s_addc_u32 s51, s25, 0
	s_add_i32 s49, s52, s8
	global_load_lds_dwordx4 v[216:217], off
	v_lshl_add_u64 v[234:235], s[50:51], 0, v[184:185]
	s_mov_b32 m0, s49
	v_lshl_add_u64 v[236:237], s[26:27], 0, v[146:147]
	global_load_lds_dwordx4 v[234:235], off
	v_lshl_add_u64 v[234:235], s[50:51], 0, v[144:145]
	s_add_i32 m0, s49, 0x2000
	s_nop 0
	global_load_lds_dwordx4 v[234:235], off
	v_lshl_add_u64 v[234:235], s[26:27], 0, v[148:149]
	s_mov_b32 m0, s28
	s_nop 0
	global_load_lds_dwordx4 v[234:235], off
	s_mov_b32 m0, s29
	s_nop 0
	global_load_lds_dwordx4 v[236:237], off
	s_waitcnt vmcnt(8)
	s_waitcnt lgkmcnt(0)
	s_barrier
; #define PG8_STAGE(bufoff, gbase, voff) do { _Pragma("unroll") for (int _i = 0; _i < 2; ++_i) \
;         __builtin_amdgcn_global_load_lds((const unsigned*)((const char*)(gbase) + (voff)[_i]), (LAS unsigned*)(lds + (bufoff) + ldsw + _i * 8192), 16, 0, 0); } while (0)
; #define PG8_LDA(dst, b, h) do { _Pragma("unroll") for (int m = 0; m < 4; ++m) _Pragma("unroll") for (int k = 0; k < 2; ++k) dst[m][k] = *(const LAS bf16x8*)(lds + PG8_SA(b, h) + aoff + m * 2048 + k * 1024); } while (0)
; #define PG8_LDB(dst, b, h) do { _Pragma("unroll") for (int n = 0; n < 2; ++n) _Pragma("unroll") for (int k = 0; k < 2; ++k) dst[n][k] = *(const LAS bf16x8*)(lds + PG8_SB(b, h) + boff + n * 2048 + k * 1024); } while (0)
; #define PG8_MMA(ai, bj, At, Bt) do { __builtin_amdgcn_s_setprio(1); _Pragma("unroll") for (int m = 0; m < 4; ++m) _Pragma("unroll") for (int n = 0; n < 2; ++n) _Pragma("unroll") for (int k = 0; k < 2; ++k) \
;         acc[ai][bj][m][n] = __builtin_amdgcn_mfma_f32_16x16x32_bf16(Bt[n][k], At[m][k], acc[ai][bj][m][n], 0, 0, 0); __builtin_amdgcn_s_setprio(0); } while (0)
; #define PG8_WAIT_V(n) asm volatile("s_waitcnt vmcnt(" #n ")" ::: "memory")
; #define PG8_WAIT_L(n) asm volatile("s_waitcnt lgkmcnt(" #n ")" ::: "memory")
; #define PG8_BAR __builtin_amdgcn_s_barrier()
; #define PG8_SCHED __builtin_amdgcn_sched_barrier(0)
; template <class Epi, class Sched>
; __device__ __forceinline__ void gemm_phase(LAS unsigned char* lds, const Gemm g, const Sched& S, const Epi& E) {
;     ...
;             PG8_WAIT_V(8); PG8_WAIT_L(0); PG8_BAR; PG8_MMA(1, 0, At, B0); PG8_MMA(1, 1, At, B1); PG8_BAR; PG8_SCHED;
;             PG8_LDB(B0, 1, 0); PG8_LDB(B1, 1, 1); PG8_SCHED; PG8_LDA(At, 1, 0); PG8_STAGE(PG8_SA(0, 1), a2 + hstep, voffA);
;             PG8_WAIT_V(8); PG8_WAIT_L(0); PG8_BAR; PG8_MMA(0, 0, At, B0); PG8_MMA(0, 1, At, B1); PG8_BAR; PG8_SCHED;
	s_waitcnt lgkmcnt(0)
	v_mfma_f32_16x16x32_bf16 v[60:63], v[128:131], v[176:179], v[60:63]
	v_mfma_f32_16x16x32_bf16 v[56:59], v[136:139], v[176:179], v[56:59]
	v_mfma_f32_16x16x32_bf16 v[44:47], v[128:131], v[196:199], v[44:47]
	v_mfma_f32_16x16x32_bf16 v[40:43], v[136:139], v[196:199], v[40:43]
	v_mfma_f32_16x16x32_bf16 v[28:31], v[128:131], v[204:207], v[28:31]
	v_mfma_f32_16x16x32_bf16 v[24:27], v[136:139], v[204:207], v[24:27]
	v_mfma_f32_16x16x32_bf16 v[12:15], v[128:131], v[212:215], v[12:15]
	v_mfma_f32_16x16x32_bf16 v[8:11], v[136:139], v[212:215], v[8:11]
	v_mfma_f32_16x16x32_bf16 v[60:63], v[132:135], v[192:195], v[60:63]
	v_mfma_f32_16x16x32_bf16 v[56:59], v[140:143], v[192:195], v[56:59]
	v_mfma_f32_16x16x32_bf16 v[44:47], v[132:135], v[200:203], v[44:47]
	v_mfma_f32_16x16x32_bf16 v[40:43], v[140:143], v[200:203], v[40:43]
	v_mfma_f32_16x16x32_bf16 v[28:31], v[132:135], v[208:211], v[28:31]
	v_mfma_f32_16x16x32_bf16 v[24:27], v[140:143], v[208:211], v[24:27]
	v_mfma_f32_16x16x32_bf16 v[12:15], v[132:135], v[230:233], v[12:15]
	v_mfma_f32_16x16x32_bf16 v[8:11], v[140:143], v[230:233], v[8:11]
	v_mfma_f32_16x16x32_bf16 v[48:51], v[154:157], v[176:179], v[48:51]
	v_mfma_f32_16x16x32_bf16 v[52:55], v[168:171], v[176:179], v[52:55]
	v_mfma_f32_16x16x32_bf16 v[32:35], v[154:157], v[196:199], v[32:35]
	v_mfma_f32_16x16x32_bf16 v[36:39], v[168:171], v[196:199], v[36:39]
	v_mfma_f32_16x16x32_bf16 v[16:19], v[154:157], v[204:207], v[16:19]
	v_mfma_f32_16x16x32_bf16 v[20:23], v[168:171], v[204:207], v[20:23]
	v_mfma_f32_16x16x32_bf16 v[0:3], v[154:157], v[212:215], v[0:3]
	v_mfma_f32_16x16x32_bf16 v[4:7], v[168:171], v[212:215], v[4:7]
	v_mfma_f32_16x16x32_bf16 v[48:51], v[164:167], v[192:195], v[48:51]
	v_mfma_f32_16x16x32_bf16 v[52:55], v[172:175], v[192:195], v[52:55]
	v_mfma_f32_16x16x32_bf16 v[32:35], v[164:167], v[200:203], v[32:35]
	v_mfma_f32_16x16x32_bf16 v[36:39], v[172:175], v[200:203], v[36:39]
	v_mfma_f32_16x16x32_bf16 v[16:19], v[164:167], v[208:211], v[16:19]
	v_mfma_f32_16x16x32_bf16 v[20:23], v[172:175], v[208:211], v[20:23]
	v_mfma_f32_16x16x32_bf16 v[0:3], v[164:167], v[230:233], v[0:3]
	v_mfma_f32_16x16x32_bf16 v[4:7], v[172:175], v[230:233], v[4:7]
	s_barrier
	s_add_i32 s49, 0, 0x18000
	s_add_i32 s50, 0, 0x1c000
	v_add_u32_e32 v140, s49, v162
	v_add_u32_e32 v172, s50, v162
	ds_read_b128 v[128:131], v140
	ds_read_b128 v[132:135], v140 offset:1024
	ds_read_b128 v[136:139], v140 offset:2048
	ds_read_b128 v[140:143], v140 offset:3072
	ds_read_b128 v[154:157], v172
	ds_read_b128 v[164:167], v172 offset:1024
	ds_read_b128 v[168:171], v172 offset:2048
	ds_read_b128 v[172:175], v172 offset:3072
	s_add_u32 s26, s26, 0x40000
	s_addc_u32 s27, s27, 0
	s_mov_b32 m0, s30
	v_lshl_add_u64 v[238:239], s[26:27], 0, v[148:149]
	ds_read_b128 v[176:179], v163 offset:32768
	ds_read_b128 v[192:195], v163 offset:33792
	ds_read_b128 v[196:199], v163 offset:34816
	ds_read_b128 v[200:203], v163 offset:35840
	ds_read_b128 v[204:207], v163 offset:36864
	ds_read_b128 v[208:211], v163 offset:37888
	ds_read_b128 v[212:215], v163 offset:38912
	ds_read_b128 v[230:233], v163 offset:39936
	global_load_lds_dwordx4 v[238:239], off
	v_lshl_add_u64 v[238:239], s[26:27], 0, v[146:147]
	s_mov_b32 m0, s31
	s_nop 0
	global_load_lds_dwordx4 v[238:239], off
	s_waitcnt vmcnt(8)
	s_waitcnt lgkmcnt(0)
	s_barrier
	s_waitcnt lgkmcnt(0)
	v_mfma_f32_16x16x32_bf16 v[124:127], v[128:131], v[176:179], v[124:127]
	v_mfma_f32_16x16x32_bf16 v[120:123], v[136:139], v[176:179], v[120:123]
	v_mfma_f32_16x16x32_bf16 v[108:111], v[128:131], v[196:199], v[108:111]
	v_mfma_f32_16x16x32_bf16 v[104:107], v[136:139], v[196:199], v[104:107]
	v_mfma_f32_16x16x32_bf16 v[92:95], v[128:131], v[204:207], v[92:95]
	v_mfma_f32_16x16x32_bf16 v[88:91], v[136:139], v[204:207], v[88:91]
	v_mfma_f32_16x16x32_bf16 v[76:79], v[128:131], v[212:215], v[76:79]
	v_mfma_f32_16x16x32_bf16 v[72:75], v[136:139], v[212:215], v[72:75]
	v_mfma_f32_16x16x32_bf16 v[124:127], v[132:135], v[192:195], v[124:127]
	v_mfma_f32_16x16x32_bf16 v[120:123], v[140:143], v[192:195], v[120:123]
	v_mfma_f32_16x16x32_bf16 v[108:111], v[132:135], v[200:203], v[108:111]
	v_mfma_f32_16x16x32_bf16 v[104:107], v[140:143], v[200:203], v[104:107]
	v_mfma_f32_16x16x32_bf16 v[92:95], v[132:135], v[208:211], v[92:95]
	v_mfma_f32_16x16x32_bf16 v[88:91], v[140:143], v[208:211], v[88:91]
	v_mfma_f32_16x16x32_bf16 v[76:79], v[132:135], v[230:233], v[76:79]
	v_mfma_f32_16x16x32_bf16 v[72:75], v[140:143], v[230:233], v[72:75]
	v_mfma_f32_16x16x32_bf16 v[112:115], v[154:157], v[176:179], v[112:115]
	v_mfma_f32_16x16x32_bf16 v[116:119], v[168:171], v[176:179], v[116:119]
	v_mfma_f32_16x16x32_bf16 v[96:99], v[154:157], v[196:199], v[96:99]
	v_mfma_f32_16x16x32_bf16 v[100:103], v[168:171], v[196:199], v[100:103]
	v_mfma_f32_16x16x32_bf16 v[80:83], v[154:157], v[204:207], v[80:83]
	v_mfma_f32_16x16x32_bf16 v[84:87], v[168:171], v[204:207], v[84:87]
	v_mfma_f32_16x16x32_bf16 v[64:67], v[154:157], v[212:215], v[64:67]
	v_mfma_f32_16x16x32_bf16 v[68:71], v[168:171], v[212:215], v[68:71]
	v_mfma_f32_16x16x32_bf16 v[112:115], v[164:167], v[192:195], v[112:115]
	v_mfma_f32_16x16x32_bf16 v[116:119], v[172:175], v[192:195], v[116:119]
	v_mfma_f32_16x16x32_bf16 v[96:99], v[164:167], v[200:203], v[96:99]
	v_mfma_f32_16x16x32_bf16 v[100:103], v[172:175], v[200:203], v[100:103]
	v_mfma_f32_16x16x32_bf16 v[80:83], v[164:167], v[208:211], v[80:83]
	v_mfma_f32_16x16x32_bf16 v[84:87], v[172:175], v[208:211], v[84:87]
	v_mfma_f32_16x16x32_bf16 v[64:67], v[164:167], v[230:233], v[64:67]
	v_mfma_f32_16x16x32_bf16 v[68:71], v[172:175], v[230:233], v[68:71]
	s_barrier
; #define PG8_STAGE(bufoff, gbase, voff) do { _Pragma("unroll") for (int _i = 0; _i < 2; ++_i) \
;         __builtin_amdgcn_global_load_lds((const unsigned*)((const char*)(gbase) + (voff)[_i]), (LAS unsigned*)(lds + (bufoff) + ldsw + _i * 8192), 16, 0, 0); } while (0)
; #define PG8_LDA(dst, b, h) do { _Pragma("unroll") for (int m = 0; m < 4; ++m) _Pragma("unroll") for (int k = 0; k < 2; ++k) dst[m][k] = *(const LAS bf16x8*)(lds + PG8_SA(b, h) + aoff + m * 2048 + k * 1024); } while (0)
; #define PG8_MMA(ai, bj, At, Bt) do { __builtin_amdgcn_s_setprio(1); _Pragma("unroll") for (int m = 0; m < 4; ++m) _Pragma("unroll") for (int n = 0; n < 2; ++n) _Pragma("unroll") for (int k = 0; k < 2; ++k) \
;         acc[ai][bj][m][n] = __builtin_amdgcn_mfma_f32_16x16x32_bf16(Bt[n][k], At[m][k], acc[ai][bj][m][n], 0, 0, 0); __builtin_amdgcn_s_setprio(0); } while (0)
; #define PG8_WAIT_V(n) asm volatile("s_waitcnt vmcnt(" #n ")" ::: "memory")
; #define PG8_WAIT_L(n) asm volatile("s_waitcnt lgkmcnt(" #n ")" ::: "memory")
; #define PG8_BAR __builtin_amdgcn_s_barrier()
; #define PG8_SCHED __builtin_amdgcn_sched_barrier(0)
; template <class Epi, class Sched>
; __device__ __forceinline__ void gemm_phase(LAS unsigned char* lds, const Gemm g, const Sched& S, const Epi& E) {
;     ...
;             PG8_LDA(At, 1, 1); PG8_STAGE(PG8_SB(1, 0), b3, voffB); PG8_STAGE(PG8_SB(1, 1), b3 + hstep, voffB); PG8_STAGE(PG8_SA(1, 0), a3, voffA);
;             PG8_WAIT_V(8); PG8_WAIT_L(0); PG8_BAR; PG8_MMA(1, 0, At, B0); PG8_MMA(1, 1, At, B1); PG8_BAR; PG8_SCHED;
;         }
;         if (wr == 0) PG8_BAR;
	s_add_i32 s26, s49, s8
	v_lshl_add_u64 v[158:159], v[158:159], 0, s[84:85]
	s_mov_b32 m0, s26
	ds_read_b128 v[176:179], v163 offset:49152
	ds_read_b128 v[192:195], v163 offset:50176
	ds_read_b128 v[196:199], v163 offset:51200
	ds_read_b128 v[200:203], v163 offset:52224
	ds_read_b128 v[204:207], v163 offset:53248
	ds_read_b128 v[208:211], v163 offset:54272
	ds_read_b128 v[212:215], v163 offset:55296
	ds_read_b128 v[230:233], v163 offset:56320
	global_load_lds_dwordx4 v[158:159], off
	s_add_i32 m0, s26, 0x2000
	s_add_u32 s24, s24, 0x40080
	v_lshl_add_u64 v[158:159], v[216:217], 0, s[84:85]
	s_addc_u32 s25, s25, 0
	s_add_i32 s26, s50, s8
	global_load_lds_dwordx4 v[158:159], off
	v_lshl_add_u64 v[158:159], s[24:25], 0, v[184:185]
	s_mov_b32 m0, s26
	s_nop 0
	global_load_lds_dwordx4 v[158:159], off
	v_lshl_add_u64 v[158:159], s[24:25], 0, v[144:145]
	s_add_i32 m0, s26, 0x2000
	s_nop 0
	global_load_lds_dwordx4 v[158:159], off
	v_lshl_add_u64 v[158:159], v[234:235], 0, s[84:85]
	s_mov_b32 m0, s36
	s_nop 0
	global_load_lds_dwordx4 v[158:159], off
	v_lshl_add_u64 v[158:159], v[236:237], 0, s[84:85]
	s_mov_b32 m0, s37
	s_nop 0
	global_load_lds_dwordx4 v[158:159], off
	s_waitcnt vmcnt(8)
	s_waitcnt lgkmcnt(0)
	s_barrier
	s_waitcnt lgkmcnt(0)
	v_mfma_f32_16x16x32_bf16 v[60:63], v[128:131], v[176:179], v[60:63]
	v_mfma_f32_16x16x32_bf16 v[56:59], v[136:139], v[176:179], v[56:59]
	v_mfma_f32_16x16x32_bf16 v[44:47], v[128:131], v[196:199], v[44:47]
	v_mfma_f32_16x16x32_bf16 v[40:43], v[136:139], v[196:199], v[40:43]
	v_mfma_f32_16x16x32_bf16 v[28:31], v[128:131], v[204:207], v[28:31]
	v_mfma_f32_16x16x32_bf16 v[24:27], v[136:139], v[204:207], v[24:27]
	v_mfma_f32_16x16x32_bf16 v[12:15], v[128:131], v[212:215], v[12:15]
	v_mfma_f32_16x16x32_bf16 v[8:11], v[136:139], v[212:215], v[8:11]
	v_mfma_f32_16x16x32_bf16 v[60:63], v[132:135], v[192:195], v[60:63]
	v_mfma_f32_16x16x32_bf16 v[56:59], v[140:143], v[192:195], v[56:59]
	v_mfma_f32_16x16x32_bf16 v[44:47], v[132:135], v[200:203], v[44:47]
	v_mfma_f32_16x16x32_bf16 v[40:43], v[140:143], v[200:203], v[40:43]
	v_mfma_f32_16x16x32_bf16 v[28:31], v[132:135], v[208:211], v[28:31]
	v_mfma_f32_16x16x32_bf16 v[24:27], v[140:143], v[208:211], v[24:27]
	v_mfma_f32_16x16x32_bf16 v[12:15], v[132:135], v[230:233], v[12:15]
	v_mfma_f32_16x16x32_bf16 v[8:11], v[140:143], v[230:233], v[8:11]
	v_mfma_f32_16x16x32_bf16 v[48:51], v[154:157], v[176:179], v[48:51]
	v_mfma_f32_16x16x32_bf16 v[52:55], v[168:171], v[176:179], v[52:55]
	v_mfma_f32_16x16x32_bf16 v[32:35], v[154:157], v[196:199], v[32:35]
	v_mfma_f32_16x16x32_bf16 v[36:39], v[168:171], v[196:199], v[36:39]
	v_mfma_f32_16x16x32_bf16 v[16:19], v[154:157], v[204:207], v[16:19]
	v_mfma_f32_16x16x32_bf16 v[20:23], v[168:171], v[204:207], v[20:23]
	v_mfma_f32_16x16x32_bf16 v[0:3], v[154:157], v[212:215], v[0:3]
	v_mfma_f32_16x16x32_bf16 v[4:7], v[168:171], v[212:215], v[4:7]
	v_mfma_f32_16x16x32_bf16 v[48:51], v[164:167], v[192:195], v[48:51]
	v_mfma_f32_16x16x32_bf16 v[52:55], v[172:175], v[192:195], v[52:55]
	v_mfma_f32_16x16x32_bf16 v[32:35], v[164:167], v[200:203], v[32:35]
	v_mfma_f32_16x16x32_bf16 v[36:39], v[172:175], v[200:203], v[36:39]
	v_mfma_f32_16x16x32_bf16 v[16:19], v[164:167], v[208:211], v[16:19]
	v_mfma_f32_16x16x32_bf16 v[20:23], v[172:175], v[208:211], v[20:23]
	v_mfma_f32_16x16x32_bf16 v[0:3], v[164:167], v[230:233], v[0:3]
	v_mfma_f32_16x16x32_bf16 v[4:7], v[172:175], v[230:233], v[4:7]
	s_barrier
	s_add_i32 s48, s48, 2
	s_add_u32 s22, s22, 0x100
	s_addc_u32 s23, s23, 0
	s_add_u32 s46, s46, 0x100
	s_addc_u32 s47, s47, 0
	s_cmp_gt_u32 s48, 13
	s_cbranch_scc0 .LBB0_744
	s_and_b64 vcc, exec, s[6:7]
	s_cbranch_vccz .LBB0_747
	s_barrier
